# GEMM K-loop heads aligned to 64 bytes (code placement)
# speedup vs baseline: 1.0083x; 1.0083x over previous
; #define STAGE_A(b, h, kt) do { _Pragma("unroll") for (int _i = 0; _i < 2; ++_i) \
;     __builtin_amdgcn_global_load_lds((const unsigned*)(Ab[h] + (kt) * BK + offA[GATHER ? h : 0][_i]), \
;       (__attribute__((address_space(3))) unsigned*)((char*)SA(b, h) + tid * 16 + _i * 8192), 16, 0, 0); } while (0)
; #define STAGE_B(b, h, kt) do { _Pragma("unroll") for (int _i = 0; _i < 2; ++_i) \
;     __builtin_amdgcn_global_load_lds((const unsigned*)(Bb[h] + (kt) * BK + offB[_i]), \
;       (__attribute__((address_space(3))) unsigned*)((char*)SB(b, h) + tid * 16 + _i * 8192), 16, 0, 0); } while (0)
; #define WAIT_V(n) asm volatile("s_waitcnt vmcnt(" #n ")" ::: "memory")
; #define BAR __builtin_amdgcn_s_barrier()
; template <int EPI, bool GATHER>
; DEVINL void gemm_tile(const Params& p, const u16* __restrict__ A, int lda, const int* __restrict__ rowidx,
;                       const u16* __restrict__ Bt, int ldb, int K, int brow, int bcol, int orow, int ocol) {
;     ...
;   const int wid = tid >> 6, lane = tid & 63, wr = wid >> 2, wc = wid & 3, fr = lane & 15, fq = lane >> 4;
;   f32x4 acc[2][2][4][2] = {};
;   bf16x8 At[4][2], B0[2][2], B1[2][2];
;   const int nt = K / BK;
;   STAGE_B(0, 0, 0); STAGE_A(0, 0, 0);
;   STAGE_B(0, 1, 0); STAGE_A(0, 1, 0);
;   if (wr == 1) BAR;
;   WAIT_V(4); BAR;
;   STAGE_B(1, 0, 1); STAGE_A(1, 0, 1); STAGE_B(1, 1, 1);
;   WAIT_V(6); BAR;
;   for (int t = 0; t < nt - 2; t += 2) {
.LBB0_226:
	s_or_b64 exec, exec, s[6:7]
	v_add_u32_e32 v160, s45, v17
	v_add_u32_e32 v161, 0x2000, v160
	v_readfirstlane_b32 s49, v160
	v_lshl_add_u64 v[0:1], v[0:1], 0, s[8:9]
	s_mov_b32 m0, s49
	v_readfirstlane_b32 s49, v161
	v_add_u32_e32 v162, 0x8000, v153
	s_waitcnt vmcnt(4)
	s_barrier
	global_load_lds_dwordx4 v[0:1], off
	v_lshl_add_u64 v[0:1], v[2:3], 0, s[8:9]
	s_mov_b32 m0, s49
	v_readfirstlane_b32 s49, v162
	v_add_u32_e32 v163, 0xa000, v153
	global_load_lds_dwordx4 v[0:1], off
	v_lshl_add_u64 v[0:1], v[6:7], 0, s[8:9]
	s_mov_b32 m0, s49
	v_readfirstlane_b32 s49, v163
	v_add_u32_e32 v164, s46, v17
	global_load_lds_dwordx4 v[0:1], off
	v_lshl_add_u64 v[0:1], v[4:5], 0, s[8:9]
	s_mov_b32 m0, s49
	v_readfirstlane_b32 s49, v164
	v_add_u32_e32 v165, 0x2000, v164
	global_load_lds_dwordx4 v[0:1], off
	v_lshl_add_u64 v[0:1], v[8:9], 0, s[8:9]
	s_mov_b32 m0, s49
	v_readfirstlane_b32 s49, v165
	global_load_lds_dwordx4 v[0:1], off
	v_lshl_add_u64 v[0:1], v[10:11], 0, s[8:9]
	s_mov_b32 m0, s49
	v_and_b32_e32 v143, 15, v141
	global_load_lds_dwordx4 v[0:1], off
	v_bfe_u32 v144, v141, 4, 2
	v_lshlrev_b32_e32 v2, 2, v141
	v_lshlrev_b32_e32 v0, 4, v144
	v_lshlrev_b32_e32 v1, 6, v143
	v_and_b32_e32 v2, 32, v2
	v_bitop3_b32 v1, v0, v2, v1 bitop3:0x36
	v_add_u32_e32 v5, s43, v1
	v_add_u32_e32 v6, s44, v1
	v_add_u32_e32 v7, s45, v1
	v_add_u32_e32 v8, s46, v1
	v_add_u32_e32 v10, 16, v1
	v_lshlrev_b32_e32 v1, 6, v141
	s_movk_i32 s49, 0x3c0
	v_and_or_b32 v0, v1, s49, v0
	v_xad_u32 v11, v0, v2, 16
	v_lshlrev_b32_e32 v0, 14, v16
	v_and_b32_e32 v0, 0xffff8000, v0
	v_lshlrev_b32_e32 v2, 14, v12
	v_lshl_add_u32 v0, v18, 11, v0
	v_and_b32_e32 v2, 0xffff8000, v2
	v_or_b32_e32 v0, v0, v19
	v_lshl_add_u32 v2, v13, 11, v2
	s_and_b32 s6, s41, 0xffffff00
	v_add_u32_sdwa v0, v0, sext(v20) dst_sel:DWORD dst_unused:UNUSED_PAD src0_sel:DWORD src1_sel:WORD_0
	v_or_b32_e32 v2, v2, v14
	s_lshl_b32 s4, s3, 12
	s_ashr_i32 s7, s6, 31
	v_ashrrev_i32_e32 v1, 31, v0
	v_add_u32_sdwa v2, v2, sext(v15) dst_sel:DWORD dst_unused:UNUSED_PAD src0_sel:DWORD src1_sel:WORD_0
	s_and_b32 s4, s4, 0x1f00000
	s_lshl_b64 s[6:7], s[6:7], 12
	v_bfe_u32 v142, v141, 6, 2
	s_waitcnt vmcnt(6)
	v_lshlrev_b32_e32 v9, 13, v21
	v_lshlrev_b64 v[0:1], 1, v[0:1]
	v_ashrrev_i32_e32 v3, 31, v2
	v_lshlrev_b32_e32 v4, 12, v142
	v_lshlrev_b32_e32 v145, 6, v21
	v_or_b32_e32 v17, 0x800, v9
	v_or_b32_e32 v21, 0x1000, v9
	v_or_b32_e32 v22, 0x1800, v9
	v_lshl_add_u64 v[132:133], s[4:5], 0, v[0:1]
	v_lshlrev_b64 v[2:3], 1, v[2:3]
	v_lshl_add_u64 v[136:137], s[6:7], 0, v[0:1]
	v_mov_b32_e32 v0, 0
	v_lshl_add_u64 v[134:135], s[4:5], 0, v[2:3]
	v_lshl_add_u64 v[138:139], s[6:7], 0, v[2:3]
	s_mov_b32 s4, -2
	v_add_u32_e32 v167, v5, v4
	v_add_u32_e32 v149, v10, v9
	v_add_u32_e32 v148, v11, v17
	v_add_u32_e32 v147, v11, v21
	v_add_u32_e32 v146, v11, v22
	v_add_u32_e32 v166, v6, v4
	v_add_u32_e32 v156, v7, v4
	v_add_u32_e32 v151, v8, v4
	s_mov_b64 vcc, s[92:93]
	v_mov_b32_e32 v1, v0
	v_mov_b32_e32 v2, v0
	v_mov_b32_e32 v3, v0
	v_mov_b32_e32 v4, v0
	v_mov_b32_e32 v5, v0
	v_mov_b32_e32 v6, v0
	v_mov_b32_e32 v7, v0
	v_mov_b32_e32 v8, v0
	v_mov_b32_e32 v9, v0
	v_mov_b32_e32 v10, v0
	v_mov_b32_e32 v11, v0
	v_mov_b32_e32 v12, v0
	v_mov_b32_e32 v13, v0
	v_mov_b32_e32 v14, v0
	v_mov_b32_e32 v15, v0
	v_mov_b32_e32 v16, v0
	v_mov_b32_e32 v17, v0
	v_mov_b32_e32 v18, v0
	v_mov_b32_e32 v19, v0
	v_mov_b32_e32 v20, v0
	v_mov_b32_e32 v21, v0
	v_mov_b32_e32 v22, v0
	v_mov_b32_e32 v23, v0
	v_mov_b32_e32 v24, v0
	v_mov_b32_e32 v25, v0
	v_mov_b32_e32 v26, v0
	v_mov_b32_e32 v27, v0
	v_mov_b32_e32 v28, v0
	v_mov_b32_e32 v29, v0
	v_mov_b32_e32 v30, v0
	v_mov_b32_e32 v31, v0
	v_mov_b32_e32 v32, v0
	v_mov_b32_e32 v33, v0
	v_mov_b32_e32 v34, v0
	v_mov_b32_e32 v35, v0
	v_mov_b32_e32 v36, v0
	v_mov_b32_e32 v37, v0
	v_mov_b32_e32 v38, v0
	v_mov_b32_e32 v39, v0
	v_mov_b32_e32 v40, v0
	v_mov_b32_e32 v41, v0
	v_mov_b32_e32 v42, v0
	v_mov_b32_e32 v43, v0
	v_mov_b32_e32 v44, v0
	v_mov_b32_e32 v45, v0
	v_mov_b32_e32 v46, v0
	v_mov_b32_e32 v47, v0
	v_mov_b32_e32 v48, v0
	v_mov_b32_e32 v49, v0
	v_mov_b32_e32 v50, v0
	v_mov_b32_e32 v51, v0
	v_mov_b32_e32 v52, v0
	v_mov_b32_e32 v53, v0
	v_mov_b32_e32 v54, v0
	v_mov_b32_e32 v55, v0
	v_mov_b32_e32 v56, v0
	v_mov_b32_e32 v57, v0
	v_mov_b32_e32 v58, v0
	v_mov_b32_e32 v59, v0
	v_mov_b32_e32 v60, v0
	v_mov_b32_e32 v61, v0
	v_mov_b32_e32 v62, v0
	v_mov_b32_e32 v63, v0
	v_mov_b32_e32 v64, v0
	v_mov_b32_e32 v65, v0
	v_mov_b32_e32 v66, v0
	v_mov_b32_e32 v67, v0
	v_mov_b32_e32 v68, v0
	v_mov_b32_e32 v69, v0
	v_mov_b32_e32 v70, v0
	v_mov_b32_e32 v71, v0
	v_mov_b32_e32 v72, v0
	v_mov_b32_e32 v73, v0
	v_mov_b32_e32 v74, v0
	v_mov_b32_e32 v75, v0
	v_mov_b32_e32 v76, v0
	v_mov_b32_e32 v77, v0
	v_mov_b32_e32 v78, v0
	v_mov_b32_e32 v79, v0
	v_mov_b32_e32 v80, v0
	v_mov_b32_e32 v81, v0
	v_mov_b32_e32 v82, v0
	v_mov_b32_e32 v83, v0
	v_mov_b32_e32 v84, v0
	v_mov_b32_e32 v85, v0
	v_mov_b32_e32 v86, v0
	v_mov_b32_e32 v87, v0
	v_mov_b32_e32 v88, v0
	v_mov_b32_e32 v89, v0
	v_mov_b32_e32 v90, v0
	v_mov_b32_e32 v91, v0
	v_mov_b32_e32 v92, v0
	v_mov_b32_e32 v93, v0
	v_mov_b32_e32 v94, v0
	v_mov_b32_e32 v95, v0
	v_mov_b32_e32 v96, v0
	v_mov_b32_e32 v97, v0
	v_mov_b32_e32 v98, v0
	v_mov_b32_e32 v99, v0
	v_mov_b32_e32 v100, v0
	v_mov_b32_e32 v101, v0
	v_mov_b32_e32 v102, v0
	v_mov_b32_e32 v103, v0
	v_mov_b32_e32 v104, v0
	v_mov_b32_e32 v105, v0
	v_mov_b32_e32 v106, v0
	v_mov_b32_e32 v107, v0
	v_mov_b32_e32 v108, v0
	v_mov_b32_e32 v109, v0
	v_mov_b32_e32 v110, v0
	v_mov_b32_e32 v111, v0
	v_mov_b32_e32 v112, v0
	v_mov_b32_e32 v113, v0
	v_mov_b32_e32 v114, v0
	v_mov_b32_e32 v115, v0
	v_mov_b32_e32 v116, v0
	v_mov_b32_e32 v117, v0
	v_mov_b32_e32 v118, v0
	v_mov_b32_e32 v119, v0
	v_mov_b32_e32 v120, v0
	v_mov_b32_e32 v121, v0
	v_mov_b32_e32 v122, v0
	v_mov_b32_e32 v123, v0
	v_mov_b32_e32 v124, v0
	v_mov_b32_e32 v125, v0
	v_mov_b32_e32 v126, v0
	v_mov_b32_e32 v127, v0
	s_barrier
	.p2alignl 6, 3212836864

; #define STAGE_A(b, h, kt) do { _Pragma("unroll") for (int _i = 0; _i < 2; ++_i) \
;     __builtin_amdgcn_global_load_lds((const unsigned*)(Ab[h] + (kt) * BK + offA[GATHER ? h : 0][_i]), \
;       (__attribute__((address_space(3))) unsigned*)((char*)SA(b, h) + tid * 16 + _i * 8192), 16, 0, 0); } while (0)
; #define STAGE_B(b, h, kt) do { _Pragma("unroll") for (int _i = 0; _i < 2; ++_i) \
;     __builtin_amdgcn_global_load_lds((const unsigned*)(Bb[h] + (kt) * BK + offB[_i]), \
;       (__attribute__((address_space(3))) unsigned*)((char*)SB(b, h) + tid * 16 + _i * 8192), 16, 0, 0); } while (0)
; #define WAIT_V(n) asm volatile("s_waitcnt vmcnt(" #n ")" ::: "memory")
; #define BAR __builtin_amdgcn_s_barrier()
; template <int EPI, bool GATHER>
; DEVINL void gemm_tile(const Params& p, const u16* __restrict__ A, int lda, const int* __restrict__ rowidx,
;                       const u16* __restrict__ Bt, int ldb, int K, int brow, int bcol, int orow, int ocol) {
;     ...
;   const int wid = tid >> 6, lane = tid & 63, wr = wid >> 2, wc = wid & 3, fr = lane & 15, fq = lane >> 4;
;   f32x4 acc[2][2][4][2] = {};
;   bf16x8 At[4][2], B0[2][2], B1[2][2];
;   const int nt = K / BK;
;   STAGE_B(0, 0, 0); STAGE_A(0, 0, 0);
;   STAGE_B(0, 1, 0); STAGE_A(0, 1, 0);
;   if (wr == 1) BAR;
;   WAIT_V(4); BAR;
;   STAGE_B(1, 0, 1); STAGE_A(1, 0, 1); STAGE_B(1, 1, 1);
;   WAIT_V(6); BAR;
;   for (int t = 0; t < nt - 2; t += 2) {
.LBB0_612:
	s_or_b64 exec, exec, s[38:39]
	s_lshl_b32 s1, s51, 11
	v_add_u32_e32 v160, s43, v17
	s_and_b32 s12, s1, 0xf80000
	v_readfirstlane_b32 s1, v160
	v_add_u32_e32 v161, 0x2000, v160
	v_lshl_add_u64 v[0:1], v[0:1], 0, s[14:15]
	s_mov_b32 m0, s1
	v_readfirstlane_b32 s1, v161
	v_add_u32_e32 v162, 0x8000, v153
	s_waitcnt vmcnt(4)
	s_barrier
	global_load_lds_dwordx4 v[0:1], off
	v_lshl_add_u64 v[0:1], v[2:3], 0, s[14:15]
	s_mov_b32 m0, s1
	v_readfirstlane_b32 s1, v162
	v_add_u32_e32 v163, 0xa000, v153
	global_load_lds_dwordx4 v[0:1], off
	v_lshl_add_u64 v[0:1], v[6:7], 0, s[14:15]
	s_mov_b32 m0, s1
	v_readfirstlane_b32 s1, v163
	v_add_u32_e32 v164, s44, v17
	global_load_lds_dwordx4 v[0:1], off
	v_lshl_add_u64 v[0:1], v[4:5], 0, s[14:15]
	s_mov_b32 m0, s1
	v_readfirstlane_b32 s1, v164
	v_add_u32_e32 v165, 0x2000, v164
	global_load_lds_dwordx4 v[0:1], off
	v_lshl_add_u64 v[0:1], v[8:9], 0, s[14:15]
	s_mov_b32 m0, s1
	v_readfirstlane_b32 s1, v165
	global_load_lds_dwordx4 v[0:1], off
	v_lshl_add_u64 v[0:1], v[10:11], 0, s[14:15]
	s_mov_b32 m0, s1
	v_and_b32_e32 v143, 15, v141
	global_load_lds_dwordx4 v[0:1], off
	v_bfe_u32 v144, v141, 4, 2
	v_lshlrev_b32_e32 v2, 2, v141
	v_lshlrev_b32_e32 v0, 4, v144
	v_lshlrev_b32_e32 v1, 6, v143
	v_and_b32_e32 v2, 32, v2
	v_bitop3_b32 v1, v0, v2, v1 bitop3:0x36
	v_add_u32_e32 v5, s41, v1
	v_add_u32_e32 v6, s42, v1
	v_add_u32_e32 v7, s43, v1
	v_add_u32_e32 v8, s44, v1
	v_add_u32_e32 v10, 16, v1
	v_lshlrev_b32_e32 v1, 6, v141
	v_and_or_b32 v0, v1, s47, v0
	v_xad_u32 v11, v0, v2, 16
	v_lshlrev_b32_e32 v0, 13, v16
	v_and_b32_e32 v0, 0xffffc000, v0
	v_lshlrev_b32_e32 v2, 13, v12
	v_lshl_add_u32 v0, v18, 10, v0
	v_and_b32_e32 v2, 0xffffc000, v2
	v_or_b32_e32 v0, v0, v19
	v_lshl_add_u32 v2, v13, 10, v2
	s_and_b32 s38, s50, 0xffffff00
	v_add_u32_sdwa v0, v0, sext(v20) dst_sel:DWORD dst_unused:UNUSED_PAD src0_sel:DWORD src1_sel:WORD_0
	v_or_b32_e32 v2, v2, v14
	s_ashr_i32 s39, s38, 31
	v_ashrrev_i32_e32 v1, 31, v0
	v_add_u32_sdwa v2, v2, sext(v15) dst_sel:DWORD dst_unused:UNUSED_PAD src0_sel:DWORD src1_sel:WORD_0
	s_lshl_b64 s[38:39], s[38:39], 11
	v_bfe_u32 v142, v141, 6, 2
	s_waitcnt vmcnt(6)
	v_lshlrev_b32_e32 v9, 13, v21
	v_lshlrev_b64 v[0:1], 1, v[0:1]
	v_ashrrev_i32_e32 v3, 31, v2
	v_lshlrev_b32_e32 v4, 12, v142
	v_lshlrev_b32_e32 v145, 6, v21
	v_or_b32_e32 v17, 0x800, v9
	v_or_b32_e32 v21, 0x1000, v9
	v_or_b32_e32 v22, 0x1800, v9
	v_lshl_add_u64 v[132:133], s[12:13], 0, v[0:1]
	v_lshlrev_b64 v[2:3], 1, v[2:3]
	v_lshl_add_u64 v[136:137], s[38:39], 0, v[0:1]
	v_mov_b32_e32 v0, 0
	v_lshl_add_u64 v[134:135], s[12:13], 0, v[2:3]
	v_lshl_add_u64 v[138:139], s[38:39], 0, v[2:3]
	s_mov_b32 s1, -2
	v_add_u32_e32 v167, v5, v4
	v_add_u32_e32 v149, v10, v9
	v_add_u32_e32 v148, v11, v17
	v_add_u32_e32 v147, v11, v21
	v_add_u32_e32 v146, v11, v22
	v_add_u32_e32 v166, v6, v4
	v_add_u32_e32 v156, v7, v4
	v_add_u32_e32 v151, v8, v4
	s_mov_b64 s[38:39], s[92:93]
	v_mov_b32_e32 v1, v0
	v_mov_b32_e32 v2, v0
	v_mov_b32_e32 v3, v0
	v_mov_b32_e32 v4, v0
	v_mov_b32_e32 v5, v0
	v_mov_b32_e32 v6, v0
	v_mov_b32_e32 v7, v0
	v_mov_b32_e32 v8, v0
	v_mov_b32_e32 v9, v0
	v_mov_b32_e32 v10, v0
	v_mov_b32_e32 v11, v0
	v_mov_b32_e32 v12, v0
	v_mov_b32_e32 v13, v0
	v_mov_b32_e32 v14, v0
	v_mov_b32_e32 v15, v0
	v_mov_b32_e32 v16, v0
	v_mov_b32_e32 v17, v0
	v_mov_b32_e32 v18, v0
	v_mov_b32_e32 v19, v0
	v_mov_b32_e32 v20, v0
	v_mov_b32_e32 v21, v0
	v_mov_b32_e32 v22, v0
	v_mov_b32_e32 v23, v0
	v_mov_b32_e32 v24, v0
	v_mov_b32_e32 v25, v0
	v_mov_b32_e32 v26, v0
	v_mov_b32_e32 v27, v0
	v_mov_b32_e32 v28, v0
	v_mov_b32_e32 v29, v0
	v_mov_b32_e32 v30, v0
	v_mov_b32_e32 v31, v0
	v_mov_b32_e32 v32, v0
	v_mov_b32_e32 v33, v0
	v_mov_b32_e32 v34, v0
	v_mov_b32_e32 v35, v0
	v_mov_b32_e32 v36, v0
	v_mov_b32_e32 v37, v0
	v_mov_b32_e32 v38, v0
	v_mov_b32_e32 v39, v0
	v_mov_b32_e32 v40, v0
	v_mov_b32_e32 v41, v0
	v_mov_b32_e32 v42, v0
	v_mov_b32_e32 v43, v0
	v_mov_b32_e32 v44, v0
	v_mov_b32_e32 v45, v0
	v_mov_b32_e32 v46, v0
	v_mov_b32_e32 v47, v0
	v_mov_b32_e32 v48, v0
	v_mov_b32_e32 v49, v0
	v_mov_b32_e32 v50, v0
	v_mov_b32_e32 v51, v0
	v_mov_b32_e32 v52, v0
	v_mov_b32_e32 v53, v0
	v_mov_b32_e32 v54, v0
	v_mov_b32_e32 v55, v0
	v_mov_b32_e32 v56, v0
	v_mov_b32_e32 v57, v0
	v_mov_b32_e32 v58, v0
	v_mov_b32_e32 v59, v0
	v_mov_b32_e32 v60, v0
	v_mov_b32_e32 v61, v0
	v_mov_b32_e32 v62, v0
	v_mov_b32_e32 v63, v0
	v_mov_b32_e32 v64, v0
	v_mov_b32_e32 v65, v0
	v_mov_b32_e32 v66, v0
	v_mov_b32_e32 v67, v0
	v_mov_b32_e32 v68, v0
	v_mov_b32_e32 v69, v0
	v_mov_b32_e32 v70, v0
	v_mov_b32_e32 v71, v0
	v_mov_b32_e32 v72, v0
	v_mov_b32_e32 v73, v0
	v_mov_b32_e32 v74, v0
	v_mov_b32_e32 v75, v0
	v_mov_b32_e32 v76, v0
	v_mov_b32_e32 v77, v0
	v_mov_b32_e32 v78, v0
	v_mov_b32_e32 v79, v0
	v_mov_b32_e32 v80, v0
	v_mov_b32_e32 v81, v0
	v_mov_b32_e32 v82, v0
	v_mov_b32_e32 v83, v0
	v_mov_b32_e32 v84, v0
	v_mov_b32_e32 v85, v0
	v_mov_b32_e32 v86, v0
	v_mov_b32_e32 v87, v0
	v_mov_b32_e32 v88, v0
	v_mov_b32_e32 v89, v0
	v_mov_b32_e32 v90, v0
	v_mov_b32_e32 v91, v0
	v_mov_b32_e32 v92, v0
	v_mov_b32_e32 v93, v0
	v_mov_b32_e32 v94, v0
	v_mov_b32_e32 v95, v0
	v_mov_b32_e32 v96, v0
	v_mov_b32_e32 v97, v0
	v_mov_b32_e32 v98, v0
	v_mov_b32_e32 v99, v0
	v_mov_b32_e32 v100, v0
	v_mov_b32_e32 v101, v0
	v_mov_b32_e32 v102, v0
	v_mov_b32_e32 v103, v0
	v_mov_b32_e32 v104, v0
	v_mov_b32_e32 v105, v0
	v_mov_b32_e32 v106, v0
	v_mov_b32_e32 v107, v0
	v_mov_b32_e32 v108, v0
	v_mov_b32_e32 v109, v0
	v_mov_b32_e32 v110, v0
	v_mov_b32_e32 v111, v0
	v_mov_b32_e32 v112, v0
	v_mov_b32_e32 v113, v0
	v_mov_b32_e32 v114, v0
	v_mov_b32_e32 v115, v0
	v_mov_b32_e32 v116, v0
	v_mov_b32_e32 v117, v0
	v_mov_b32_e32 v118, v0
	v_mov_b32_e32 v119, v0
	v_mov_b32_e32 v120, v0
	v_mov_b32_e32 v121, v0
	v_mov_b32_e32 v122, v0
	v_mov_b32_e32 v123, v0
	v_mov_b32_e32 v124, v0
	v_mov_b32_e32 v125, v0
	v_mov_b32_e32 v126, v0
	v_mov_b32_e32 v127, v0
	s_barrier
	.p2alignl 6, 3212836864

; #define STAGE_A(b, h, kt) do { _Pragma("unroll") for (int _i = 0; _i < 2; ++_i) \
;     __builtin_amdgcn_global_load_lds((const unsigned*)(Ab[h] + (kt) * BK + offA[GATHER ? h : 0][_i]), \
;       (__attribute__((address_space(3))) unsigned*)((char*)SA(b, h) + tid * 16 + _i * 8192), 16, 0, 0); } while (0)
; #define STAGE_B(b, h, kt) do { _Pragma("unroll") for (int _i = 0; _i < 2; ++_i) \
;     __builtin_amdgcn_global_load_lds((const unsigned*)(Bb[h] + (kt) * BK + offB[_i]), \
;       (__attribute__((address_space(3))) unsigned*)((char*)SB(b, h) + tid * 16 + _i * 8192), 16, 0, 0); } while (0)
; #define WAIT_V(n) asm volatile("s_waitcnt vmcnt(" #n ")" ::: "memory")
; #define BAR __builtin_amdgcn_s_barrier()
; template <int EPI, bool GATHER>
; DEVINL void gemm_tile(const Params& p, const u16* __restrict__ A, int lda, const int* __restrict__ rowidx,
;                       const u16* __restrict__ Bt, int ldb, int K, int brow, int bcol, int orow, int ocol) {
;     ...
;   const int wid = tid >> 6, lane = tid & 63, wr = wid >> 2, wc = wid & 3, fr = lane & 15, fq = lane >> 4;
;   f32x4 acc[2][2][4][2] = {};
;   bf16x8 At[4][2], B0[2][2], B1[2][2];
;   const int nt = K / BK;
;   STAGE_B(0, 0, 0); STAGE_A(0, 0, 0);
;   STAGE_B(0, 1, 0); STAGE_A(0, 1, 0);
;   if (wr == 1) BAR;
;   WAIT_V(4); BAR;
;   STAGE_B(1, 0, 1); STAGE_A(1, 0, 1); STAGE_B(1, 1, 1);
;   WAIT_V(6); BAR;
;   for (int t = 0; t < nt - 2; t += 2) {
.LBB0_620:
	s_or_b64 exec, exec, s[38:39]
	s_lshl_b32 s1, s3, 11
	v_add_u32_e32 v160, s43, v17
	s_and_b32 s14, s1, 0xf80000
	v_readfirstlane_b32 s1, v160
	v_add_u32_e32 v161, 0x2000, v160
	v_lshl_add_u64 v[0:1], v[0:1], 0, s[16:17]
	s_mov_b32 m0, s1
	v_readfirstlane_b32 s1, v161
	v_add_u32_e32 v162, 0x8000, v153
	s_waitcnt vmcnt(4)
	s_barrier
	global_load_lds_dwordx4 v[0:1], off
	v_lshl_add_u64 v[0:1], v[2:3], 0, s[16:17]
	s_mov_b32 m0, s1
	v_readfirstlane_b32 s1, v162
	v_add_u32_e32 v163, 0xa000, v153
	global_load_lds_dwordx4 v[0:1], off
	v_lshl_add_u64 v[0:1], v[6:7], 0, s[16:17]
	s_mov_b32 m0, s1
	v_readfirstlane_b32 s1, v163
	v_add_u32_e32 v164, s44, v17
	global_load_lds_dwordx4 v[0:1], off
	v_lshl_add_u64 v[0:1], v[4:5], 0, s[16:17]
	s_mov_b32 m0, s1
	v_readfirstlane_b32 s1, v164
	v_add_u32_e32 v165, 0x2000, v164
	global_load_lds_dwordx4 v[0:1], off
	v_lshl_add_u64 v[0:1], v[8:9], 0, s[16:17]
	s_mov_b32 m0, s1
	v_readfirstlane_b32 s1, v165
	global_load_lds_dwordx4 v[0:1], off
	v_lshl_add_u64 v[0:1], v[10:11], 0, s[16:17]
	s_mov_b32 m0, s1
	v_and_b32_e32 v143, 15, v141
	global_load_lds_dwordx4 v[0:1], off
	v_bfe_u32 v144, v141, 4, 2
	v_lshlrev_b32_e32 v2, 2, v141
	v_lshlrev_b32_e32 v0, 4, v144
	v_lshlrev_b32_e32 v1, 6, v143
	v_and_b32_e32 v2, 32, v2
	v_bitop3_b32 v1, v0, v2, v1 bitop3:0x36
	v_add_u32_e32 v5, s41, v1
	v_add_u32_e32 v6, s42, v1
	v_add_u32_e32 v7, s43, v1
	v_add_u32_e32 v8, s44, v1
	v_add_u32_e32 v10, 16, v1
	v_lshlrev_b32_e32 v1, 6, v141
	v_and_or_b32 v0, v1, s49, v0
	v_xad_u32 v11, v0, v2, 16
	v_lshlrev_b32_e32 v0, 13, v16
	v_and_b32_e32 v0, 0xffffc000, v0
	v_lshlrev_b32_e32 v2, 13, v12
	v_lshl_add_u32 v0, v18, 10, v0
	v_and_b32_e32 v2, 0xffffc000, v2
	v_or_b32_e32 v0, v0, v19
	v_lshl_add_u32 v2, v13, 10, v2
	s_and_b32 s38, s53, 0xffffff00
	v_add_u32_sdwa v0, v0, sext(v20) dst_sel:DWORD dst_unused:UNUSED_PAD src0_sel:DWORD src1_sel:WORD_0
	v_or_b32_e32 v2, v2, v14
	s_ashr_i32 s39, s38, 31
	v_ashrrev_i32_e32 v1, 31, v0
	v_add_u32_sdwa v2, v2, sext(v15) dst_sel:DWORD dst_unused:UNUSED_PAD src0_sel:DWORD src1_sel:WORD_0
	s_lshl_b64 s[38:39], s[38:39], 11
	v_bfe_u32 v142, v141, 6, 2
	s_waitcnt vmcnt(6)
	v_lshlrev_b32_e32 v9, 13, v21
	v_lshlrev_b64 v[0:1], 1, v[0:1]
	v_ashrrev_i32_e32 v3, 31, v2
	v_lshlrev_b32_e32 v4, 12, v142
	v_lshlrev_b32_e32 v145, 6, v21
	v_or_b32_e32 v17, 0x800, v9
	v_or_b32_e32 v21, 0x1000, v9
	v_or_b32_e32 v22, 0x1800, v9
	v_lshl_add_u64 v[132:133], s[14:15], 0, v[0:1]
	v_lshlrev_b64 v[2:3], 1, v[2:3]
	v_lshl_add_u64 v[136:137], s[38:39], 0, v[0:1]
	v_mov_b32_e32 v0, 0
	v_lshl_add_u64 v[134:135], s[14:15], 0, v[2:3]
	v_lshl_add_u64 v[138:139], s[38:39], 0, v[2:3]
	s_mov_b32 s1, -2
	v_add_u32_e32 v167, v5, v4
	v_add_u32_e32 v149, v10, v9
	v_add_u32_e32 v148, v11, v17
	v_add_u32_e32 v147, v11, v21
	v_add_u32_e32 v146, v11, v22
	v_add_u32_e32 v166, v6, v4
	v_add_u32_e32 v156, v7, v4
	v_add_u32_e32 v151, v8, v4
	s_mov_b64 s[38:39], s[92:93]
	v_mov_b32_e32 v1, v0
	v_mov_b32_e32 v2, v0
	v_mov_b32_e32 v3, v0
	v_mov_b32_e32 v4, v0
	v_mov_b32_e32 v5, v0
	v_mov_b32_e32 v6, v0
	v_mov_b32_e32 v7, v0
	v_mov_b32_e32 v8, v0
	v_mov_b32_e32 v9, v0
	v_mov_b32_e32 v10, v0
	v_mov_b32_e32 v11, v0
	v_mov_b32_e32 v12, v0
	v_mov_b32_e32 v13, v0
	v_mov_b32_e32 v14, v0
	v_mov_b32_e32 v15, v0
	v_mov_b32_e32 v16, v0
	v_mov_b32_e32 v17, v0
	v_mov_b32_e32 v18, v0
	v_mov_b32_e32 v19, v0
	v_mov_b32_e32 v20, v0
	v_mov_b32_e32 v21, v0
	v_mov_b32_e32 v22, v0
	v_mov_b32_e32 v23, v0
	v_mov_b32_e32 v24, v0
	v_mov_b32_e32 v25, v0
	v_mov_b32_e32 v26, v0
	v_mov_b32_e32 v27, v0
	v_mov_b32_e32 v28, v0
	v_mov_b32_e32 v29, v0
	v_mov_b32_e32 v30, v0
	v_mov_b32_e32 v31, v0
	v_mov_b32_e32 v32, v0
	v_mov_b32_e32 v33, v0
	v_mov_b32_e32 v34, v0
	v_mov_b32_e32 v35, v0
	v_mov_b32_e32 v36, v0
	v_mov_b32_e32 v37, v0
	v_mov_b32_e32 v38, v0
	v_mov_b32_e32 v39, v0
	v_mov_b32_e32 v40, v0
	v_mov_b32_e32 v41, v0
	v_mov_b32_e32 v42, v0
	v_mov_b32_e32 v43, v0
	v_mov_b32_e32 v44, v0
	v_mov_b32_e32 v45, v0
	v_mov_b32_e32 v46, v0
	v_mov_b32_e32 v47, v0
	v_mov_b32_e32 v48, v0
	v_mov_b32_e32 v49, v0
	v_mov_b32_e32 v50, v0
	v_mov_b32_e32 v51, v0
	v_mov_b32_e32 v52, v0
	v_mov_b32_e32 v53, v0
	v_mov_b32_e32 v54, v0
	v_mov_b32_e32 v55, v0
	v_mov_b32_e32 v56, v0
	v_mov_b32_e32 v57, v0
	v_mov_b32_e32 v58, v0
	v_mov_b32_e32 v59, v0
	v_mov_b32_e32 v60, v0
	v_mov_b32_e32 v61, v0
	v_mov_b32_e32 v62, v0
	v_mov_b32_e32 v63, v0
	v_mov_b32_e32 v64, v0
	v_mov_b32_e32 v65, v0
	v_mov_b32_e32 v66, v0
	v_mov_b32_e32 v67, v0
	v_mov_b32_e32 v68, v0
	v_mov_b32_e32 v69, v0
	v_mov_b32_e32 v70, v0
	v_mov_b32_e32 v71, v0
	v_mov_b32_e32 v72, v0
	v_mov_b32_e32 v73, v0
	v_mov_b32_e32 v74, v0
	v_mov_b32_e32 v75, v0
	v_mov_b32_e32 v76, v0
	v_mov_b32_e32 v77, v0
	v_mov_b32_e32 v78, v0
	v_mov_b32_e32 v79, v0
	v_mov_b32_e32 v80, v0
	v_mov_b32_e32 v81, v0
	v_mov_b32_e32 v82, v0
	v_mov_b32_e32 v83, v0
	v_mov_b32_e32 v84, v0
	v_mov_b32_e32 v85, v0
	v_mov_b32_e32 v86, v0
	v_mov_b32_e32 v87, v0
	v_mov_b32_e32 v88, v0
	v_mov_b32_e32 v89, v0
	v_mov_b32_e32 v90, v0
	v_mov_b32_e32 v91, v0
	v_mov_b32_e32 v92, v0
	v_mov_b32_e32 v93, v0
	v_mov_b32_e32 v94, v0
	v_mov_b32_e32 v95, v0
	v_mov_b32_e32 v96, v0
	v_mov_b32_e32 v97, v0
	v_mov_b32_e32 v98, v0
	v_mov_b32_e32 v99, v0
	v_mov_b32_e32 v100, v0
	v_mov_b32_e32 v101, v0
	v_mov_b32_e32 v102, v0
	v_mov_b32_e32 v103, v0
	v_mov_b32_e32 v104, v0
	v_mov_b32_e32 v105, v0
	v_mov_b32_e32 v106, v0
	v_mov_b32_e32 v107, v0
	v_mov_b32_e32 v108, v0
	v_mov_b32_e32 v109, v0
	v_mov_b32_e32 v110, v0
	v_mov_b32_e32 v111, v0
	v_mov_b32_e32 v112, v0
	v_mov_b32_e32 v113, v0
	v_mov_b32_e32 v114, v0
	v_mov_b32_e32 v115, v0
	v_mov_b32_e32 v116, v0
	v_mov_b32_e32 v117, v0
	v_mov_b32_e32 v118, v0
	v_mov_b32_e32 v119, v0
	v_mov_b32_e32 v120, v0
	v_mov_b32_e32 v121, v0
	v_mov_b32_e32 v122, v0
	v_mov_b32_e32 v123, v0
	v_mov_b32_e32 v124, v0
	v_mov_b32_e32 v125, v0
	v_mov_b32_e32 v126, v0
	v_mov_b32_e32 v127, v0
	s_barrier
	.p2alignl 6, 3212836864

; #define STAGE_A(b, h, kt) do { _Pragma("unroll") for (int _i = 0; _i < 2; ++_i) \
;     __builtin_amdgcn_global_load_lds((const unsigned*)(Ab[h] + (kt) * BK + offA[GATHER ? h : 0][_i]), \
;       (__attribute__((address_space(3))) unsigned*)((char*)SA(b, h) + tid * 16 + _i * 8192), 16, 0, 0); } while (0)
; #define STAGE_B(b, h, kt) do { _Pragma("unroll") for (int _i = 0; _i < 2; ++_i) \
;     __builtin_amdgcn_global_load_lds((const unsigned*)(Bb[h] + (kt) * BK + offB[_i]), \
;       (__attribute__((address_space(3))) unsigned*)((char*)SB(b, h) + tid * 16 + _i * 8192), 16, 0, 0); } while (0)
; #define WAIT_V(n) asm volatile("s_waitcnt vmcnt(" #n ")" ::: "memory")
; #define BAR __builtin_amdgcn_s_barrier()
; template <int EPI, bool GATHER>
; DEVINL void gemm_tile(const Params& p, const u16* __restrict__ A, int lda, const int* __restrict__ rowidx,
;                       const u16* __restrict__ Bt, int ldb, int K, int brow, int bcol, int orow, int ocol) {
;     ...
;   const int wid = tid >> 6, lane = tid & 63, wr = wid >> 2, wc = wid & 3, fr = lane & 15, fq = lane >> 4;
;   f32x4 acc[2][2][4][2] = {};
;   bf16x8 At[4][2], B0[2][2], B1[2][2];
;   const int nt = K / BK;
;   STAGE_B(0, 0, 0); STAGE_A(0, 0, 0);
;   STAGE_B(0, 1, 0); STAGE_A(0, 1, 0);
;   if (wr == 1) BAR;
;   WAIT_V(4); BAR;
;   STAGE_B(1, 0, 1); STAGE_A(1, 0, 1); STAGE_B(1, 1, 1);
;   WAIT_V(6); BAR;
;   for (int t = 0; t < nt - 2; t += 2) {
.LBB0_681:
	s_or_b64 exec, exec, s[26:27]
	v_add_u32_e32 v160, s37, v17
	v_add_u32_e32 v161, 0x2000, v160
	v_readfirstlane_b32 s23, v160
	v_lshl_add_u64 v[0:1], v[0:1], 0, s[4:5]
	s_mov_b32 m0, s23
	v_readfirstlane_b32 s23, v161
	v_add_u32_e32 v162, 0x8000, v153
	s_waitcnt vmcnt(4)
	s_barrier
	global_load_lds_dwordx4 v[0:1], off
	v_lshl_add_u64 v[0:1], v[2:3], 0, s[4:5]
	s_mov_b32 m0, s23
	v_readfirstlane_b32 s23, v162
	v_add_u32_e32 v163, 0xa000, v153
	global_load_lds_dwordx4 v[0:1], off
	v_lshl_add_u64 v[0:1], v[6:7], 0, s[4:5]
	s_mov_b32 m0, s23
	v_readfirstlane_b32 s23, v163
	v_add_u32_e32 v164, s38, v17
	global_load_lds_dwordx4 v[0:1], off
	v_lshl_add_u64 v[0:1], v[4:5], 0, s[4:5]
	s_mov_b32 m0, s23
	v_readfirstlane_b32 s23, v164
	v_add_u32_e32 v165, 0x2000, v164
	global_load_lds_dwordx4 v[0:1], off
	v_lshl_add_u64 v[0:1], v[8:9], 0, s[4:5]
	s_mov_b32 m0, s23
	v_readfirstlane_b32 s23, v165
	global_load_lds_dwordx4 v[0:1], off
	v_lshl_add_u64 v[0:1], v[10:11], 0, s[4:5]
	s_mov_b32 m0, s23
	v_and_b32_e32 v144, 15, v141
	global_load_lds_dwordx4 v[0:1], off
	v_bfe_u32 v143, v141, 4, 2
	v_lshlrev_b32_e32 v2, 2, v141
	v_lshlrev_b32_e32 v0, 4, v143
	v_lshlrev_b32_e32 v1, 6, v144
	v_and_b32_e32 v2, 32, v2
	v_bitop3_b32 v1, v0, v2, v1 bitop3:0x36
	v_add_u32_e32 v5, s35, v1
	v_add_u32_e32 v6, s36, v1
	v_add_u32_e32 v7, s37, v1
	v_add_u32_e32 v8, s38, v1
	v_add_u32_e32 v10, 16, v1
	v_lshlrev_b32_e32 v1, 6, v141
	v_and_or_b32 v0, v1, s39, v0
	v_xad_u32 v11, v0, v2, 16
	v_lshlrev_b32_e32 v0, 14, v16
	v_and_b32_e32 v0, 0xffff8000, v0
	v_lshlrev_b32_e32 v2, 14, v12
	v_lshl_add_u32 v0, v18, 11, v0
	v_and_b32_e32 v2, 0xffff8000, v2
	v_or_b32_e32 v0, v0, v19
	v_lshl_add_u32 v2, v13, 11, v2
	s_and_b32 s26, s41, 0xffffff00
	v_add_u32_sdwa v0, v0, sext(v20) dst_sel:DWORD dst_unused:UNUSED_PAD src0_sel:DWORD src1_sel:WORD_0
	v_or_b32_e32 v2, v2, v14
	s_lshl_b32 s0, s31, 12
	s_ashr_i32 s27, s26, 31
	v_ashrrev_i32_e32 v1, 31, v0
	v_add_u32_sdwa v2, v2, sext(v15) dst_sel:DWORD dst_unused:UNUSED_PAD src0_sel:DWORD src1_sel:WORD_0
	s_and_b32 s0, s0, 0x1f00000
	s_lshl_b64 s[26:27], s[26:27], 12
	v_bfe_u32 v142, v141, 6, 2
	s_waitcnt vmcnt(6)
	v_lshlrev_b32_e32 v9, 13, v21
	v_lshlrev_b64 v[0:1], 1, v[0:1]
	v_ashrrev_i32_e32 v3, 31, v2
	v_lshlrev_b32_e32 v4, 12, v142
	v_lshlrev_b32_e32 v145, 6, v21
	v_or_b32_e32 v17, 0x800, v9
	v_or_b32_e32 v21, 0x1000, v9
	v_or_b32_e32 v22, 0x1800, v9
	v_lshl_add_u64 v[132:133], s[0:1], 0, v[0:1]
	v_lshlrev_b64 v[2:3], 1, v[2:3]
	v_lshl_add_u64 v[136:137], s[26:27], 0, v[0:1]
	v_mov_b32_e32 v0, 0
	v_lshl_add_u64 v[134:135], s[0:1], 0, v[2:3]
	v_lshl_add_u64 v[138:139], s[26:27], 0, v[2:3]
	s_mov_b32 s0, -2
	v_add_u32_e32 v167, v5, v4
	v_add_u32_e32 v149, v10, v9
	v_add_u32_e32 v148, v11, v17
	v_add_u32_e32 v147, v11, v21
	v_add_u32_e32 v146, v11, v22
	v_add_u32_e32 v166, v6, v4
	v_add_u32_e32 v156, v7, v4
	v_add_u32_e32 v151, v8, v4
	s_mov_b64 s[26:27], s[92:93]
	v_mov_b32_e32 v1, v0
	v_mov_b32_e32 v2, v0
	v_mov_b32_e32 v3, v0
	v_mov_b32_e32 v4, v0
	v_mov_b32_e32 v5, v0
	v_mov_b32_e32 v6, v0
	v_mov_b32_e32 v7, v0
	v_mov_b32_e32 v8, v0
	v_mov_b32_e32 v9, v0
	v_mov_b32_e32 v10, v0
	v_mov_b32_e32 v11, v0
	v_mov_b32_e32 v12, v0
	v_mov_b32_e32 v13, v0
	v_mov_b32_e32 v14, v0
	v_mov_b32_e32 v15, v0
	v_mov_b32_e32 v16, v0
	v_mov_b32_e32 v17, v0
	v_mov_b32_e32 v18, v0
	v_mov_b32_e32 v19, v0
	v_mov_b32_e32 v20, v0
	v_mov_b32_e32 v21, v0
	v_mov_b32_e32 v22, v0
	v_mov_b32_e32 v23, v0
	v_mov_b32_e32 v24, v0
	v_mov_b32_e32 v25, v0
	v_mov_b32_e32 v26, v0
	v_mov_b32_e32 v27, v0
	v_mov_b32_e32 v28, v0
	v_mov_b32_e32 v29, v0
	v_mov_b32_e32 v30, v0
	v_mov_b32_e32 v31, v0
	v_mov_b32_e32 v32, v0
	v_mov_b32_e32 v33, v0
	v_mov_b32_e32 v34, v0
	v_mov_b32_e32 v35, v0
	v_mov_b32_e32 v36, v0
	v_mov_b32_e32 v37, v0
	v_mov_b32_e32 v38, v0
	v_mov_b32_e32 v39, v0
	v_mov_b32_e32 v40, v0
	v_mov_b32_e32 v41, v0
	v_mov_b32_e32 v42, v0
	v_mov_b32_e32 v43, v0
	v_mov_b32_e32 v44, v0
	v_mov_b32_e32 v45, v0
	v_mov_b32_e32 v46, v0
	v_mov_b32_e32 v47, v0
	v_mov_b32_e32 v48, v0
	v_mov_b32_e32 v49, v0
	v_mov_b32_e32 v50, v0
	v_mov_b32_e32 v51, v0
	v_mov_b32_e32 v52, v0
	v_mov_b32_e32 v53, v0
	v_mov_b32_e32 v54, v0
	v_mov_b32_e32 v55, v0
	v_mov_b32_e32 v56, v0
	v_mov_b32_e32 v57, v0
	v_mov_b32_e32 v58, v0
	v_mov_b32_e32 v59, v0
	v_mov_b32_e32 v60, v0
	v_mov_b32_e32 v61, v0
	v_mov_b32_e32 v62, v0
	v_mov_b32_e32 v63, v0
	v_mov_b32_e32 v64, v0
	v_mov_b32_e32 v65, v0
	v_mov_b32_e32 v66, v0
	v_mov_b32_e32 v67, v0
	v_mov_b32_e32 v68, v0
	v_mov_b32_e32 v69, v0
	v_mov_b32_e32 v70, v0
	v_mov_b32_e32 v71, v0
	v_mov_b32_e32 v72, v0
	v_mov_b32_e32 v73, v0
	v_mov_b32_e32 v74, v0
	v_mov_b32_e32 v75, v0
	v_mov_b32_e32 v76, v0
	v_mov_b32_e32 v77, v0
	v_mov_b32_e32 v78, v0
	v_mov_b32_e32 v79, v0
	v_mov_b32_e32 v80, v0
	v_mov_b32_e32 v81, v0
	v_mov_b32_e32 v82, v0
	v_mov_b32_e32 v83, v0
	v_mov_b32_e32 v84, v0
	v_mov_b32_e32 v85, v0
	v_mov_b32_e32 v86, v0
	v_mov_b32_e32 v87, v0
	v_mov_b32_e32 v88, v0
	v_mov_b32_e32 v89, v0
	v_mov_b32_e32 v90, v0
	v_mov_b32_e32 v91, v0
	v_mov_b32_e32 v92, v0
	v_mov_b32_e32 v93, v0
	v_mov_b32_e32 v94, v0
	v_mov_b32_e32 v95, v0
	v_mov_b32_e32 v96, v0
	v_mov_b32_e32 v97, v0
	v_mov_b32_e32 v98, v0
	v_mov_b32_e32 v99, v0
	v_mov_b32_e32 v100, v0
	v_mov_b32_e32 v101, v0
	v_mov_b32_e32 v102, v0
	v_mov_b32_e32 v103, v0
	v_mov_b32_e32 v104, v0
	v_mov_b32_e32 v105, v0
	v_mov_b32_e32 v106, v0
	v_mov_b32_e32 v107, v0
	v_mov_b32_e32 v108, v0
	v_mov_b32_e32 v109, v0
	v_mov_b32_e32 v110, v0
	v_mov_b32_e32 v111, v0
	v_mov_b32_e32 v112, v0
	v_mov_b32_e32 v113, v0
	v_mov_b32_e32 v114, v0
	v_mov_b32_e32 v115, v0
	v_mov_b32_e32 v116, v0
	v_mov_b32_e32 v117, v0
	v_mov_b32_e32 v118, v0
	v_mov_b32_e32 v119, v0
	v_mov_b32_e32 v120, v0
	v_mov_b32_e32 v121, v0
	v_mov_b32_e32 v122, v0
	v_mov_b32_e32 v123, v0
	v_mov_b32_e32 v124, v0
	v_mov_b32_e32 v125, v0
	v_mov_b32_e32 v126, v0
	v_mov_b32_e32 v127, v0
	s_barrier
	.p2alignl 6, 3212836864

; #define STAGE_A(b, h, kt) do { _Pragma("unroll") for (int _i = 0; _i < 2; ++_i) \
;     __builtin_amdgcn_global_load_lds((const unsigned*)(Ab[h] + (kt) * BK + offA[GATHER ? h : 0][_i]), \
;       (__attribute__((address_space(3))) unsigned*)((char*)SA(b, h) + tid * 16 + _i * 8192), 16, 0, 0); } while (0)
; #define STAGE_B(b, h, kt) do { _Pragma("unroll") for (int _i = 0; _i < 2; ++_i) \
;     __builtin_amdgcn_global_load_lds((const unsigned*)(Bb[h] + (kt) * BK + offB[_i]), \
;       (__attribute__((address_space(3))) unsigned*)((char*)SB(b, h) + tid * 16 + _i * 8192), 16, 0, 0); } while (0)
; #define WAIT_V(n) asm volatile("s_waitcnt vmcnt(" #n ")" ::: "memory")
; #define BAR __builtin_amdgcn_s_barrier()
; template <int EPI, bool GATHER>
; DEVINL void gemm_tile(const Params& p, const u16* __restrict__ A, int lda, const int* __restrict__ rowidx,
;                       const u16* __restrict__ Bt, int ldb, int K, int brow, int bcol, int orow, int ocol) {
;     ...
;       if (GATHER) offA[h][i] = rowidx[brow + h * HALF + R] * lda + C;
;       else offA[h][i] = R * lda + C;
;     ...
;   const int wid = tid >> 6, lane = tid & 63, wr = wid >> 2, wc = wid & 3, fr = lane & 15, fq = lane >> 4;
;   f32x4 acc[2][2][4][2] = {};
;   bf16x8 At[4][2], B0[2][2], B1[2][2];
;   const int nt = K / BK;
;   STAGE_B(0, 0, 0); STAGE_A(0, 0, 0);
;   STAGE_B(0, 1, 0); STAGE_A(0, 1, 0);
;   if (wr == 1) BAR;
;   WAIT_V(4); BAR;
;   STAGE_B(1, 0, 1); STAGE_A(1, 0, 1); STAGE_B(1, 1, 1);
;   WAIT_V(6); BAR;
;   for (int t = 0; t < nt - 2; t += 2) {
.LBB0_972:
	s_or_b64 exec, exec, s[38:39]
	v_add_u32_e32 v164, s41, v12
	s_lshr_b32 s38, s46, 5
	v_readfirstlane_b32 s50, v164
	v_add_u32_e32 v165, 0x2000, v164
	s_and_b32 s38, s38, 7
	v_lshl_add_u64 v[8:9], v[8:9], 0, s[22:23]
	s_mov_b32 m0, s50
	v_readfirstlane_b32 s50, v165
	v_add_u32_e32 v166, 0x8000, v157
	s_and_b32 s39, s45, 7
	s_lshl_b32 s38, s38, 20
	s_waitcnt vmcnt(4)
	s_barrier
	global_load_lds_dwordx4 v[8:9], off
	v_lshl_add_u64 v[8:9], v[10:11], 0, s[22:23]
	s_mov_b32 m0, s50
	v_lshlrev_b64 v[6:7], 1, v[6:7]
	v_readfirstlane_b32 s50, v166
	v_add_u32_e32 v167, 0xa000, v157
	global_load_lds_dwordx4 v[8:9], off
	v_lshl_add_u64 v[8:9], s[16:17], 0, v[6:7]
	s_mov_b32 m0, s50
	v_lshlrev_b64 v[4:5], 1, v[4:5]
	v_readfirstlane_b32 s50, v167
	s_add_u32 s6, s6, 0x80080
	v_add_u32_e32 v168, s42, v12
	global_load_lds_dwordx4 v[8:9], off
	v_lshl_add_u64 v[8:9], s[16:17], 0, v[4:5]
	s_mov_b32 m0, s50
	s_addc_u32 s7, s7, 0
	v_readfirstlane_b32 s50, v168
	global_load_lds_dwordx4 v[8:9], off
	v_lshl_add_u64 v[8:9], s[6:7], 0, v[0:1]
	s_mov_b32 m0, s50
	v_add_u32_e32 v169, 0x2000, v168
	global_load_lds_dwordx4 v[8:9], off
	v_lshl_add_u64 v[8:9], s[6:7], 0, v[2:3]
	v_readfirstlane_b32 s6, v169
	s_mov_b32 m0, s6
	s_add_i32 s6, s49, s39
	global_load_lds_dwordx4 v[8:9], off
	s_ashr_i32 s7, s6, 31
	s_lshl_b64 s[6:7], s[6:7], 23
	v_and_b32_e32 v149, 15, v145
	v_bfe_u32 v146, v145, 4, 2
	v_lshlrev_b32_e32 v11, 2, v145
	s_or_b32 s6, s6, s38
	v_lshlrev_b32_e32 v9, 4, v146
	v_lshlrev_b32_e32 v10, 6, v149
	v_and_b32_e32 v11, 32, v11
	v_lshlrev_b32_e32 v17, 6, v145
	s_add_u32 s6, s92, s6
	v_bfe_u32 v148, v145, 6, 2
	s_waitcnt vmcnt(6)
	v_bitop3_b32 v10, v9, v11, v10 bitop3:0x36
	v_lshlrev_b32_e32 v147, 6, v13
	v_lshlrev_b32_e32 v13, 13, v13
	v_and_or_b32 v9, v17, s43, v9
	s_addc_u32 s7, s93, s7
	v_lshlrev_b32_e32 v8, 12, v148
	v_add_u32_e32 v12, s3, v10
	v_add_u32_e32 v14, s40, v10
	v_add_u32_e32 v15, s41, v10
	v_add_u32_e32 v16, s42, v10
	v_add_u32_e32 v10, 16, v10
	v_xad_u32 v9, v9, v11, 16
	v_or_b32_e32 v11, 0x800, v13
	v_or_b32_e32 v17, 0x1000, v13
	v_or_b32_e32 v18, 0x1800, v13
	v_lshl_add_u64 v[142:143], s[6:7], 0, v[0:1]
	v_mov_b32_e32 v0, 0
	v_lshl_add_u64 v[132:133], s[92:93], 0, v[4:5]
	v_lshl_add_u64 v[134:135], s[92:93], 0, v[6:7]
	v_lshl_add_u64 v[136:137], v[128:129], 1, s[92:93]
	v_lshl_add_u64 v[138:139], v[130:131], 1, s[92:93]
	v_lshl_add_u64 v[140:141], s[6:7], 0, v[2:3]
	s_mov_b32 s38, -2
	s_mov_b64 s[6:7], 0
	v_add_u32_e32 v171, v12, v8
	v_add_u32_e32 v154, v10, v13
	v_add_u32_e32 v153, v9, v11
	v_add_u32_e32 v152, v9, v17
	v_add_u32_e32 v151, v9, v18
	v_add_u32_e32 v170, v14, v8
	v_add_u32_e32 v161, v15, v8
	v_add_u32_e32 v156, v16, v8
	v_mov_b32_e32 v1, v0
	v_mov_b32_e32 v2, v0
	v_mov_b32_e32 v3, v0
	v_mov_b32_e32 v4, v0
	v_mov_b32_e32 v5, v0
	v_mov_b32_e32 v6, v0
	v_mov_b32_e32 v7, v0
	v_mov_b32_e32 v8, v0
	v_mov_b32_e32 v9, v0
	v_mov_b32_e32 v10, v0
	v_mov_b32_e32 v11, v0
	v_mov_b32_e32 v12, v0
	v_mov_b32_e32 v13, v0
	v_mov_b32_e32 v14, v0
	v_mov_b32_e32 v15, v0
	v_mov_b32_e32 v16, v0
	v_mov_b32_e32 v17, v0
	v_mov_b32_e32 v18, v0
	v_mov_b32_e32 v19, v0
	v_mov_b32_e32 v20, v0
	v_mov_b32_e32 v21, v0
	v_mov_b32_e32 v22, v0
	v_mov_b32_e32 v23, v0
	v_mov_b32_e32 v24, v0
	v_mov_b32_e32 v25, v0
	v_mov_b32_e32 v26, v0
	v_mov_b32_e32 v27, v0
	v_mov_b32_e32 v28, v0
	v_mov_b32_e32 v29, v0
	v_mov_b32_e32 v30, v0
	v_mov_b32_e32 v31, v0
	v_mov_b32_e32 v32, v0
	v_mov_b32_e32 v33, v0
	v_mov_b32_e32 v34, v0
	v_mov_b32_e32 v35, v0
	v_mov_b32_e32 v36, v0
	v_mov_b32_e32 v37, v0
	v_mov_b32_e32 v38, v0
	v_mov_b32_e32 v39, v0
	v_mov_b32_e32 v40, v0
	v_mov_b32_e32 v41, v0
	v_mov_b32_e32 v42, v0
	v_mov_b32_e32 v43, v0
	v_mov_b32_e32 v44, v0
	v_mov_b32_e32 v45, v0
	v_mov_b32_e32 v46, v0
	v_mov_b32_e32 v47, v0
	v_mov_b32_e32 v48, v0
	v_mov_b32_e32 v49, v0
	v_mov_b32_e32 v50, v0
	v_mov_b32_e32 v51, v0
	v_mov_b32_e32 v52, v0
	v_mov_b32_e32 v53, v0
	v_mov_b32_e32 v54, v0
	v_mov_b32_e32 v55, v0
	v_mov_b32_e32 v56, v0
	v_mov_b32_e32 v57, v0
	v_mov_b32_e32 v58, v0
	v_mov_b32_e32 v59, v0
	v_mov_b32_e32 v60, v0
	v_mov_b32_e32 v61, v0
	v_mov_b32_e32 v62, v0
	v_mov_b32_e32 v63, v0
	v_mov_b32_e32 v64, v0
	v_mov_b32_e32 v65, v0
	v_mov_b32_e32 v66, v0
	v_mov_b32_e32 v67, v0
	v_mov_b32_e32 v68, v0
	v_mov_b32_e32 v69, v0
	v_mov_b32_e32 v70, v0
	v_mov_b32_e32 v71, v0
	v_mov_b32_e32 v72, v0
	v_mov_b32_e32 v73, v0
	v_mov_b32_e32 v74, v0
	v_mov_b32_e32 v75, v0
	v_mov_b32_e32 v76, v0
	v_mov_b32_e32 v77, v0
	v_mov_b32_e32 v78, v0
	v_mov_b32_e32 v79, v0
	v_mov_b32_e32 v80, v0
	v_mov_b32_e32 v81, v0
	v_mov_b32_e32 v82, v0
	v_mov_b32_e32 v83, v0
	v_mov_b32_e32 v84, v0
	v_mov_b32_e32 v85, v0
	v_mov_b32_e32 v86, v0
	v_mov_b32_e32 v87, v0
	v_mov_b32_e32 v88, v0
	v_mov_b32_e32 v89, v0
	v_mov_b32_e32 v90, v0
	v_mov_b32_e32 v91, v0
	v_mov_b32_e32 v92, v0
	v_mov_b32_e32 v93, v0
	v_mov_b32_e32 v94, v0
	v_mov_b32_e32 v95, v0
	v_mov_b32_e32 v96, v0
	v_mov_b32_e32 v97, v0
	v_mov_b32_e32 v98, v0
	v_mov_b32_e32 v99, v0
	v_mov_b32_e32 v100, v0
	v_mov_b32_e32 v101, v0
	v_mov_b32_e32 v102, v0
	v_mov_b32_e32 v103, v0
	v_mov_b32_e32 v104, v0
	v_mov_b32_e32 v105, v0
	v_mov_b32_e32 v106, v0
	v_mov_b32_e32 v107, v0
	v_mov_b32_e32 v108, v0
	v_mov_b32_e32 v109, v0
	v_mov_b32_e32 v110, v0
	v_mov_b32_e32 v111, v0
	v_mov_b32_e32 v112, v0
	v_mov_b32_e32 v113, v0
	v_mov_b32_e32 v114, v0
	v_mov_b32_e32 v115, v0
	v_mov_b32_e32 v116, v0
	v_mov_b32_e32 v117, v0
	v_mov_b32_e32 v118, v0
	v_mov_b32_e32 v119, v0
	v_mov_b32_e32 v120, v0
	v_mov_b32_e32 v121, v0
	v_mov_b32_e32 v122, v0
	v_mov_b32_e32 v123, v0
	v_mov_b32_e32 v124, v0
	v_mov_b32_e32 v125, v0
	v_mov_b32_e32 v126, v0
	v_mov_b32_e32 v127, v0
	s_barrier
	.p2alignl 6, 3212836864

; #define STAGE_A(b, h, kt) do { _Pragma("unroll") for (int _i = 0; _i < 2; ++_i) \
;     __builtin_amdgcn_global_load_lds((const unsigned*)(Ab[h] + (kt) * BK + offA[GATHER ? h : 0][_i]), \
;       (__attribute__((address_space(3))) unsigned*)((char*)SA(b, h) + tid * 16 + _i * 8192), 16, 0, 0); } while (0)
; #define STAGE_B(b, h, kt) do { _Pragma("unroll") for (int _i = 0; _i < 2; ++_i) \
;     __builtin_amdgcn_global_load_lds((const unsigned*)(Bb[h] + (kt) * BK + offB[_i]), \
;       (__attribute__((address_space(3))) unsigned*)((char*)SB(b, h) + tid * 16 + _i * 8192), 16, 0, 0); } while (0)
; #define WAIT_V(n) asm volatile("s_waitcnt vmcnt(" #n ")" ::: "memory")
; #define BAR __builtin_amdgcn_s_barrier()
; template <int EPI, bool GATHER>
; DEVINL void gemm_tile(const Params& p, const u16* __restrict__ A, int lda, const int* __restrict__ rowidx,
;                       const u16* __restrict__ Bt, int ldb, int K, int brow, int bcol, int orow, int ocol) {
;     ...
;   const int wid = tid >> 6, lane = tid & 63, wr = wid >> 2, wc = wid & 3, fr = lane & 15, fq = lane >> 4;
;   f32x4 acc[2][2][4][2] = {};
;   bf16x8 At[4][2], B0[2][2], B1[2][2];
;   const int nt = K / BK;
;   STAGE_B(0, 0, 0); STAGE_A(0, 0, 0);
;   STAGE_B(0, 1, 0); STAGE_A(0, 1, 0);
;   if (wr == 1) BAR;
;   WAIT_V(4); BAR;
;   STAGE_B(1, 0, 1); STAGE_A(1, 0, 1); STAGE_B(1, 1, 1);
;   WAIT_V(6); BAR;
;   for (int t = 0; t < nt - 2; t += 2) {
.LBB0_1033:
	s_or_b64 exec, exec, s[36:37]
	v_add_u32_e32 v160, s43, v18
	v_add_u32_e32 v161, 0x2000, v160
	v_readfirstlane_b32 s55, v160
	s_and_b32 s31, s48, 7
	s_lshl_b32 s53, s47, 11
	v_lshl_add_u64 v[4:5], v[4:5], 0, s[4:5]
	s_mov_b32 m0, s55
	v_readfirstlane_b32 s55, v161
	v_add_u32_e32 v162, 0x8000, v152
	s_lshl_b32 s36, s31, 10
	s_and_b32 s37, s39, 0x300
	s_and_b32 s53, s53, 0x380000
	s_waitcnt vmcnt(4)
	s_barrier
	global_load_lds_dwordx4 v[4:5], off
	v_lshl_add_u64 v[4:5], v[6:7], 0, s[4:5]
	s_mov_b32 m0, s55
	v_readfirstlane_b32 s55, v162
	v_add_u32_e32 v163, 0xa000, v152
	global_load_lds_dwordx4 v[4:5], off
	v_lshl_add_u64 v[4:5], v[10:11], 0, s[4:5]
	s_mov_b32 m0, s55
	v_readfirstlane_b32 s55, v163
	s_add_u32 s34, s34, 0x40080
	v_add_u32_e32 v164, s44, v18
	global_load_lds_dwordx4 v[4:5], off
	v_lshl_add_u64 v[4:5], v[8:9], 0, s[4:5]
	s_mov_b32 m0, s55
	s_addc_u32 s35, s35, 0
	v_readfirstlane_b32 s55, v164
	global_load_lds_dwordx4 v[4:5], off
	v_lshl_add_u64 v[0:1], v[0:1], 1, s[34:35]
	s_mov_b32 m0, s55
	v_add_u32_e32 v165, 0x2000, v164
	global_load_lds_dwordx4 v[0:1], off
	v_lshl_add_u64 v[0:1], v[2:3], 1, s[34:35]
	v_readfirstlane_b32 s34, v165
	s_mov_b32 m0, s34
	v_and_b32_e32 v143, 15, v141
	global_load_lds_dwordx4 v[0:1], off
	v_bfe_u32 v144, v141, 4, 2
	v_lshlrev_b32_e32 v2, 2, v141
	v_lshlrev_b32_e32 v0, 4, v144
	v_lshlrev_b32_e32 v1, 6, v143
	v_and_b32_e32 v2, 32, v2
	v_bitop3_b32 v1, v0, v2, v1 bitop3:0x36
	v_add_u32_e32 v5, s41, v1
	v_add_u32_e32 v6, s42, v1
	v_add_u32_e32 v7, s43, v1
	v_add_u32_e32 v8, s44, v1
	v_add_u32_e32 v10, 16, v1
	v_lshlrev_b32_e32 v1, 6, v141
	v_and_or_b32 v0, v1, s45, v0
	v_xad_u32 v11, v0, v2, 16
	v_lshlrev_b32_e32 v0, 13, v16
	v_lshlrev_b32_e32 v2, 13, v12
	s_lshl_b32 s34, s51, 10
	v_and_b32_e32 v0, 0xffffc000, v0
	v_and_b32_e32 v2, 0xffffc000, v2
	s_and_b32 s34, s34, 0xffffe000
	v_lshl_add_u32 v0, v17, 10, v0
	v_lshl_add_u32 v2, v13, 10, v2
	s_or_b32 s34, s34, s36
	v_or_b32_e32 v0, v0, v19
	v_or_b32_e32 v2, v2, v14
	s_or_b32 s34, s34, s37
	v_add_u32_sdwa v0, v0, sext(v20) dst_sel:DWORD dst_unused:UNUSED_PAD src0_sel:DWORD src1_sel:WORD_0
	v_add_u32_sdwa v2, v2, sext(v15) dst_sel:DWORD dst_unused:UNUSED_PAD src0_sel:DWORD src1_sel:WORD_0
	s_ashr_i32 s35, s34, 31
	v_ashrrev_i32_e32 v1, 31, v0
	v_ashrrev_i32_e32 v3, 31, v2
	s_lshl_b64 s[34:35], s[34:35], 11
	v_lshlrev_b64 v[0:1], 1, v[0:1]
	v_lshlrev_b64 v[2:3], 1, v[2:3]
	v_lshl_add_u64 v[132:133], s[34:35], 0, v[0:1]
	v_lshl_add_u64 v[134:135], s[34:35], 0, v[2:3]
	s_add_i32 s34, s50, s31
	s_ashr_i32 s35, s34, 31
	s_lshl_b64 s[34:35], s[34:35], 22
	v_bfe_u32 v142, v141, 6, 2
	s_waitcnt vmcnt(6)
	v_lshlrev_b32_e32 v9, 13, v21
	s_or_b32 s34, s34, s53
	v_lshlrev_b32_e32 v4, 12, v142
	v_lshlrev_b32_e32 v145, 6, v21
	v_or_b32_e32 v18, 0x800, v9
	v_or_b32_e32 v21, 0x1000, v9
	v_or_b32_e32 v22, 0x1800, v9
	v_lshl_add_u64 v[136:137], s[34:35], 0, v[0:1]
	v_mov_b32_e32 v0, 0
	v_lshl_add_u64 v[138:139], s[34:35], 0, v[2:3]
	s_mov_b32 s31, -2
	v_add_u32_e32 v167, v5, v4
	v_add_u32_e32 v149, v10, v9
	v_add_u32_e32 v148, v11, v18
	v_add_u32_e32 v147, v11, v21
	v_add_u32_e32 v146, v11, v22
	v_add_u32_e32 v166, v6, v4
	v_add_u32_e32 v159, v7, v4
	v_add_u32_e32 v153, v8, v4
	v_mov_b32_e32 v1, v0
	v_mov_b32_e32 v2, v0
	v_mov_b32_e32 v3, v0
	v_mov_b32_e32 v4, v0
	v_mov_b32_e32 v5, v0
	v_mov_b32_e32 v6, v0
	v_mov_b32_e32 v7, v0
	v_mov_b32_e32 v8, v0
	v_mov_b32_e32 v9, v0
	v_mov_b32_e32 v10, v0
	v_mov_b32_e32 v11, v0
	v_mov_b32_e32 v12, v0
	v_mov_b32_e32 v13, v0
	v_mov_b32_e32 v14, v0
	v_mov_b32_e32 v15, v0
	v_mov_b32_e32 v16, v0
	v_mov_b32_e32 v17, v0
	v_mov_b32_e32 v18, v0
	v_mov_b32_e32 v19, v0
	v_mov_b32_e32 v20, v0
	v_mov_b32_e32 v21, v0
	v_mov_b32_e32 v22, v0
	v_mov_b32_e32 v23, v0
	v_mov_b32_e32 v24, v0
	v_mov_b32_e32 v25, v0
	v_mov_b32_e32 v26, v0
	v_mov_b32_e32 v27, v0
	v_mov_b32_e32 v28, v0
	v_mov_b32_e32 v29, v0
	v_mov_b32_e32 v30, v0
	v_mov_b32_e32 v31, v0
	v_mov_b32_e32 v32, v0
	v_mov_b32_e32 v33, v0
	v_mov_b32_e32 v34, v0
	v_mov_b32_e32 v35, v0
	v_mov_b32_e32 v36, v0
	v_mov_b32_e32 v37, v0
	v_mov_b32_e32 v38, v0
	v_mov_b32_e32 v39, v0
	v_mov_b32_e32 v40, v0
	v_mov_b32_e32 v41, v0
	v_mov_b32_e32 v42, v0
	v_mov_b32_e32 v43, v0
	v_mov_b32_e32 v44, v0
	v_mov_b32_e32 v45, v0
	v_mov_b32_e32 v46, v0
	v_mov_b32_e32 v47, v0
	v_mov_b32_e32 v48, v0
	v_mov_b32_e32 v49, v0
	v_mov_b32_e32 v50, v0
	v_mov_b32_e32 v51, v0
	v_mov_b32_e32 v52, v0
	v_mov_b32_e32 v53, v0
	v_mov_b32_e32 v54, v0
	v_mov_b32_e32 v55, v0
	v_mov_b32_e32 v56, v0
	v_mov_b32_e32 v57, v0
	v_mov_b32_e32 v58, v0
	v_mov_b32_e32 v59, v0
	v_mov_b32_e32 v60, v0
	v_mov_b32_e32 v61, v0
	v_mov_b32_e32 v62, v0
	v_mov_b32_e32 v63, v0
	v_mov_b32_e32 v64, v0
	v_mov_b32_e32 v65, v0
	v_mov_b32_e32 v66, v0
	v_mov_b32_e32 v67, v0
	v_mov_b32_e32 v68, v0
	v_mov_b32_e32 v69, v0
	v_mov_b32_e32 v70, v0
	v_mov_b32_e32 v71, v0
	v_mov_b32_e32 v72, v0
	v_mov_b32_e32 v73, v0
	v_mov_b32_e32 v74, v0
	v_mov_b32_e32 v75, v0
	v_mov_b32_e32 v76, v0
	v_mov_b32_e32 v77, v0
	v_mov_b32_e32 v78, v0
	v_mov_b32_e32 v79, v0
	v_mov_b32_e32 v80, v0
	v_mov_b32_e32 v81, v0
	v_mov_b32_e32 v82, v0
	v_mov_b32_e32 v83, v0
	v_mov_b32_e32 v84, v0
	v_mov_b32_e32 v85, v0
	v_mov_b32_e32 v86, v0
	v_mov_b32_e32 v87, v0
	v_mov_b32_e32 v88, v0
	v_mov_b32_e32 v89, v0
	v_mov_b32_e32 v90, v0
	v_mov_b32_e32 v91, v0
	v_mov_b32_e32 v92, v0
	v_mov_b32_e32 v93, v0
	v_mov_b32_e32 v94, v0
	v_mov_b32_e32 v95, v0
	v_mov_b32_e32 v96, v0
	v_mov_b32_e32 v97, v0
	v_mov_b32_e32 v98, v0
	v_mov_b32_e32 v99, v0
	v_mov_b32_e32 v100, v0
	v_mov_b32_e32 v101, v0
	v_mov_b32_e32 v102, v0
	v_mov_b32_e32 v103, v0
	v_mov_b32_e32 v104, v0
	v_mov_b32_e32 v105, v0
	v_mov_b32_e32 v106, v0
	v_mov_b32_e32 v107, v0
	v_mov_b32_e32 v108, v0
	v_mov_b32_e32 v109, v0
	v_mov_b32_e32 v110, v0
	v_mov_b32_e32 v111, v0
	v_mov_b32_e32 v112, v0
	v_mov_b32_e32 v113, v0
	v_mov_b32_e32 v114, v0
	v_mov_b32_e32 v115, v0
	v_mov_b32_e32 v116, v0
	v_mov_b32_e32 v117, v0
	v_mov_b32_e32 v118, v0
	v_mov_b32_e32 v119, v0
	v_mov_b32_e32 v120, v0
	v_mov_b32_e32 v121, v0
	v_mov_b32_e32 v122, v0
	v_mov_b32_e32 v123, v0
	v_mov_b32_e32 v124, v0
	v_mov_b32_e32 v125, v0
	v_mov_b32_e32 v126, v0
	v_mov_b32_e32 v127, v0
	s_barrier
	.p2alignl 6, 3212836864
